# f1 + e32 encodings for the row-sum adds in the attention exp/PV segment
# baseline (speedup 1.0000x reference)
; #define LAS __attribute__((address_space(3)))
; #define MFMA32(a, b, c) __builtin_amdgcn_mfma_f32_32x32x16_bf16((a), (b), (c), 0, 0, 0)
; #define AT_EXP2(P, r) do { f32x2 dd = (f32x2){P[r], P[(r) + 1]} - mm; dd.x = __builtin_amdgcn_exp2f(dd.x); dd.y = __builtin_amdgcn_exp2f(dd.y); ssum += dd; P[r] = dd.x; P[(r) + 1] = dd.y; } while (0)
; #define AT_PACK(P, b8) ((u32x4){cvt_pk_bf16(P[(b8)], P[(b8) + 1]), cvt_pk_bf16(P[(b8) + 2], P[(b8) + 3]), cvt_pk_bf16(P[(b8) + 4], P[(b8) + 5]), cvt_pk_bf16(P[(b8) + 6], P[(b8) + 7])})
; __device__ __forceinline__ void attn_item(LAS unsigned char* lds, int b, int h, int qb, const bf16_t* Q, const bf16_t* KN, const bf16_t* KR, const bf16_t* VT, bf16_t* MIXIN, float* STAT2) {
;     ...
;             {
;                 const f32x2 mm = (f32x2){mrow, mrow}; f32x2 ssum = (f32x2){0.f, 0.f};
;                 const LAS unsigned char* vbase = lds + VOFF + vcur * VB + c * VP + hi * 16;
;     ...
; #pragma unroll
;                 for (int kk = 0; kk < 4; ++kk) {
;                     const bf16x8 vf0 = *(const LAS bf16x8*)(vbase + kk * 32), vf1 = *(const LAS bf16x8*)(vbase + 32 * VP + kk * 32);
;                     __builtin_amdgcn_sched_barrier(0);
;                     bf16x8 pfk;
;                     if (kk < 2) { AT_EXP2(p0, 8 * kk); AT_EXP2(p0, 8 * kk + 2); AT_EXP2(p0, 8 * kk + 4); AT_EXP2(p0, 8 * kk + 6); pfk = __builtin_bit_cast(bf16x8, AT_PACK(p0, 8 * kk)); }
;                     else { const int k2 = kk - 2; AT_EXP2(p1, 8 * k2); AT_EXP2(p1, 8 * k2 + 2); AT_EXP2(p1, 8 * k2 + 4); AT_EXP2(p1, 8 * k2 + 6); pfk = __builtin_bit_cast(bf16x8, AT_PACK(p1, 8 * k2)); }
;                     { const bf16x8 vf2 = *(const LAS bf16x8*)(vbase + 64 * VP + kk * 32), vf3 = *(const LAS bf16x8*)(vbase + 96 * VP + kk * 32);
;                       oT[0] = MFMA32(vf0, pfk, oT[0]); oT[1] = MFMA32(vf1, pfk, oT[1]); oT[2] = MFMA32(vf2, pfk, oT[2]); oT[3] = MFMA32(vf3, pfk, oT[3]); }
;                     __builtin_amdgcn_sched_barrier(0);
;                 }
;     ...
;                 lrow += ssum.x + ssum.y; }
.LBB0_967:
	s_mul_i32 s8, s45, 0x4800
	v_add_u32_e32 v2, s8, v220
	ds_read_b128 v[6:9], v2 offset:51200
	ds_read_b128 v[10:13], v2 offset:55808
	v_sub_f32_e32 v14, v98, v4
	v_sub_f32_e32 v15, v99, v4
	v_exp_f32_e32 v98, v14
	v_exp_f32_e32 v99, v15
	v_sub_f32_e32 v14, v100, v4
	v_sub_f32_e32 v15, v101, v4
	v_exp_f32_e32 v100, v14
	v_exp_f32_e32 v101, v15
	v_sub_f32_e32 v14, v102, v4
	v_sub_f32_e32 v15, v103, v4
	v_exp_f32_e32 v102, v14
	v_exp_f32_e32 v103, v15
	v_sub_f32_e32 v14, v104, v4
	v_sub_f32_e32 v15, v105, v4
	v_cvt_pk_bf16_f32 v16, v102, v103
	v_exp_f32_e32 v104, v14
	v_exp_f32_e32 v105, v15
	v_cvt_pk_bf16_f32 v14, v98, v99
	v_cvt_pk_bf16_f32 v15, v100, v101
	v_cvt_pk_bf16_f32 v17, v104, v105
	s_waitcnt lgkmcnt(1)
	s_nop 0
	v_mfma_f32_32x32x16_bf16 v[66:81], v[6:9], v[14:17], v[66:81]
	s_waitcnt lgkmcnt(0)
	v_mfma_f32_32x32x16_bf16 v[50:65], v[10:13], v[14:17], v[50:65]
	ds_read_b128 v[6:9], v2 offset:60416
	ds_read_b128 v[10:13], v2 offset:65024
	s_waitcnt lgkmcnt(1)
	v_mfma_f32_32x32x16_bf16 v[34:49], v[6:9], v[14:17], v[34:49]
	s_waitcnt lgkmcnt(0)
	v_mfma_f32_32x32x16_bf16 v[18:33], v[10:13], v[14:17], v[18:33]
	ds_read_b128 v[6:9], v2 offset:51232
	ds_read_b128 v[10:13], v2 offset:55840
	v_add_f32_e64 v14, v106, -v4
	v_add_f32_e64 v15, v107, -v4
	v_exp_f32_e32 v106, v14
	v_exp_f32_e32 v107, v15
	v_sub_f32_e32 v14, v108, v4
	v_sub_f32_e32 v15, v109, v4
	v_exp_f32_e32 v108, v14
	v_exp_f32_e32 v109, v15
	v_sub_f32_e32 v14, v110, v4
	v_sub_f32_e32 v15, v111, v4
	v_exp_f32_e32 v110, v14
	v_exp_f32_e32 v111, v15
	v_sub_f32_e32 v14, v112, v4
	v_sub_f32_e32 v15, v113, v4
	v_cvt_pk_bf16_f32 v16, v110, v111
	v_exp_f32_e32 v112, v14
	v_exp_f32_e32 v113, v15
	v_cvt_pk_bf16_f32 v14, v106, v107
	v_cvt_pk_bf16_f32 v15, v108, v109
	v_cvt_pk_bf16_f32 v17, v112, v113
	s_waitcnt lgkmcnt(1)
	s_nop 0
	v_mfma_f32_32x32x16_bf16 v[66:81], v[6:9], v[14:17], v[66:81]
	s_waitcnt lgkmcnt(0)
	v_mfma_f32_32x32x16_bf16 v[50:65], v[10:13], v[14:17], v[50:65]
	ds_read_b128 v[6:9], v2 offset:60448
	ds_read_b128 v[10:13], v2 offset:65056
	s_waitcnt lgkmcnt(1)
	v_mfma_f32_32x32x16_bf16 v[34:49], v[6:9], v[14:17], v[34:49]
	s_waitcnt lgkmcnt(0)
	v_mfma_f32_32x32x16_bf16 v[18:33], v[10:13], v[14:17], v[18:33]
	ds_read_b128 v[6:9], v2 offset:51264
	ds_read_b128 v[10:13], v2 offset:55872
	v_add_f32_e64 v14, v82, -v4
	v_add_f32_e64 v15, v83, -v4
	v_exp_f32_e32 v82, v14
	v_exp_f32_e32 v83, v15
	v_sub_f32_e32 v14, v84, v4
	v_sub_f32_e32 v15, v85, v4
	v_exp_f32_e32 v84, v14
	v_exp_f32_e32 v85, v15
	v_sub_f32_e32 v14, v86, v4
	v_sub_f32_e32 v15, v87, v4
	v_exp_f32_e32 v86, v14
	v_exp_f32_e32 v87, v15
	v_sub_f32_e32 v14, v88, v4
	v_sub_f32_e32 v15, v89, v4
	v_cvt_pk_bf16_f32 v16, v86, v87
	v_exp_f32_e32 v88, v14
	v_exp_f32_e32 v89, v15
	v_cvt_pk_bf16_f32 v14, v82, v83
	v_cvt_pk_bf16_f32 v15, v84, v85
	v_cvt_pk_bf16_f32 v17, v88, v89
	s_waitcnt lgkmcnt(1)
	s_nop 0
	v_mfma_f32_32x32x16_bf16 v[66:81], v[6:9], v[14:17], v[66:81]
	s_waitcnt lgkmcnt(0)
	v_mfma_f32_32x32x16_bf16 v[50:65], v[10:13], v[14:17], v[50:65]
	ds_read_b128 v[6:9], v2 offset:60480
	ds_read_b128 v[10:13], v2 offset:65088
	s_waitcnt lgkmcnt(1)
	v_mfma_f32_32x32x16_bf16 v[34:49], v[6:9], v[14:17], v[34:49]
	s_waitcnt lgkmcnt(0)
	v_mfma_f32_32x32x16_bf16 v[18:33], v[10:13], v[14:17], v[18:33]
	ds_read_b128 v[6:9], v2 offset:51296
	ds_read_b128 v[10:13], v2 offset:55904
	v_add_f32_e64 v14, v90, -v4
	v_add_f32_e64 v15, v91, -v4
	v_exp_f32_e32 v90, v14
	v_exp_f32_e32 v91, v15
	v_sub_f32_e32 v14, v92, v4
	v_sub_f32_e32 v15, v93, v4
	v_exp_f32_e32 v92, v14
	v_exp_f32_e32 v93, v15
	v_sub_f32_e32 v14, v94, v4
	v_sub_f32_e32 v15, v95, v4
	v_exp_f32_e32 v94, v14
	v_exp_f32_e32 v95, v15
	v_sub_f32_e32 v14, v96, v4
	v_sub_f32_e32 v15, v97, v4
	v_cvt_pk_bf16_f32 v16, v94, v95
	v_exp_f32_e32 v96, v14
	v_exp_f32_e32 v97, v15
	v_cvt_pk_bf16_f32 v14, v90, v91
	v_cvt_pk_bf16_f32 v15, v92, v93
	v_cvt_pk_bf16_f32 v17, v96, v97
	s_waitcnt lgkmcnt(1)
	s_nop 0
	v_mfma_f32_32x32x16_bf16 v[66:81], v[6:9], v[14:17], v[66:81]
	v_add_f32_e64 v6, v98, 0
	v_add_f32_e64 v7, v99, 0
	v_add_f32_e32 v6, v100, v6
	v_add_f32_e32 v7, v101, v7
	v_add_f32_e32 v98, v102, v6
	v_add_f32_e32 v99, v103, v7
	ds_read_b128 v[6:9], v2 offset:60512
	s_waitcnt lgkmcnt(1)
	v_mfma_f32_32x32x16_bf16 v[50:65], v[10:13], v[14:17], v[50:65]
	v_add_f32_e32 v10, v104, v98
	v_add_f32_e32 v11, v105, v99
	v_add_f32_e32 v10, v106, v10
	v_add_f32_e32 v11, v107, v11
	v_add_f32_e32 v10, v108, v10
	v_add_f32_e32 v11, v109, v11
	v_add_f32_e32 v10, v110, v10
	v_add_f32_e32 v11, v111, v11
	v_add_f32_e32 v10, v112, v10
	v_add_f32_e32 v11, v113, v11
	v_add_f32_e32 v82, v82, v10
	v_add_f32_e32 v83, v83, v11
	ds_read_b128 v[10:13], v2 offset:65120
	s_waitcnt lgkmcnt(1)
	v_mfma_f32_32x32x16_bf16 v[34:49], v[6:9], v[14:17], v[34:49]
	v_add_f32_e32 v6, v84, v82
	v_add_f32_e32 v7, v85, v83
	v_add_f32_e32 v6, v86, v6
	v_add_f32_e32 v7, v87, v7
	v_add_f32_e32 v6, v88, v6
	v_add_f32_e32 v7, v89, v7
	v_add_f32_e32 v6, v90, v6
	v_add_f32_e32 v7, v91, v7
	s_waitcnt lgkmcnt(0)
	v_mfma_f32_32x32x16_bf16 v[18:33], v[10:13], v[14:17], v[18:33]
	v_add_f32_e32 v6, v92, v6
	v_add_f32_e32 v7, v93, v7
	v_add_f32_e32 v6, v94, v6
	v_add_f32_e32 v7, v95, v7
	v_add_f32_e32 v6, v96, v6
	v_add_f32_e32 v7, v97, v7
	v_add_f32_e32 v2, v6, v7
	v_add_f32_e32 v5, v5, v2
